# v13 + grid-barrier tweak: non-leader workgroups poll the global TOPGEN release word directly instead of their XCD XGEN word (one hop fewer)
# baseline (speedup 1.0000x reference)
.LBB0_117:
	s_or_b64 exec, exec, s[14:15]
	v_cvt_f32_u32_e32 v4, v2
	s_waitcnt vmcnt(0)
	v_readfirstlane_b32 s3, v3
	v_sub_u32_e32 v3, 0, v2
	v_rcp_iflag_f32_e32 v4, v4
	v_add_u32_e32 v5, s3, v1
	v_mul_f32_e32 v4, 0x4f7ffffe, v4
	v_cvt_u32_f32_e32 v4, v4
	v_mul_lo_u32 v1, v3, v4
	v_mul_hi_u32 v1, v4, v1
	v_add_u32_e32 v1, v4, v1
	v_mul_hi_u32 v1, v5, v1
	v_mul_lo_u32 v3, v1, v2
	v_sub_u32_e32 v3, v5, v3
	v_add_u32_e32 v4, 1, v1
	v_cmp_ge_u32_e32 vcc, v3, v2
	s_nop 1
	v_cndmask_b32_e32 v1, v1, v4, vcc
	v_sub_u32_e32 v4, v3, v2
	v_cndmask_b32_e32 v3, v3, v4, vcc
	v_add_u32_e32 v4, 1, v1
	v_cmp_ge_u32_e32 vcc, v3, v2
	v_add_u32_e32 v3, 1, v5
	s_nop 0
	v_cndmask_b32_e32 v1, v1, v4, vcc
	v_mul_lo_u32 v4, v2, v1
	v_add_u32_e32 v2, v4, v2
	v_cmp_ne_u32_e32 vcc, v3, v2
	s_and_saveexec_b64 s[8:9], vcc
	s_xor_b64 s[12:13], exec, s[8:9]
	s_cbranch_execz .LBB0_131
	s_waitcnt lgkmcnt(0)
	v_mov_b32_e32 v0, 0x3100
	global_load_dword v0, v0, s[56:57] offset:1024 sc1
	s_add_u32 s16, s56, 0x3500
	s_addc_u32 s17, s57, 0
	s_waitcnt vmcnt(0)
	v_cmp_eq_u32_e32 vcc, v0, v1
	s_and_saveexec_b64 s[14:15], vcc
	s_cbranch_execz .LBB0_130
	s_mov_b32 s3, 1
	s_mov_b64 s[18:19], 0
	v_mov_b32_e32 v0, 0
	s_branch .LBB0_121

.LBB0_349:
	s_or_b64 exec, exec, s[40:41]
	v_cvt_f32_u32_e32 v4, v2
	s_waitcnt vmcnt(0)
	v_readfirstlane_b32 s6, v3
	v_sub_u32_e32 v3, 0, v2
	v_rcp_iflag_f32_e32 v4, v4
	v_add_u32_e32 v5, s6, v1
	v_mul_f32_e32 v4, 0x4f7ffffe, v4
	v_cvt_u32_f32_e32 v4, v4
	v_mul_lo_u32 v1, v3, v4
	v_mul_hi_u32 v1, v4, v1
	v_add_u32_e32 v1, v4, v1
	v_mul_hi_u32 v1, v5, v1
	v_mul_lo_u32 v3, v1, v2
	v_sub_u32_e32 v3, v5, v3
	v_add_u32_e32 v4, 1, v1
	v_cmp_ge_u32_e32 vcc, v3, v2
	s_nop 1
	v_cndmask_b32_e32 v1, v1, v4, vcc
	v_sub_u32_e32 v4, v3, v2
	v_cndmask_b32_e32 v3, v3, v4, vcc
	v_add_u32_e32 v4, 1, v1
	v_cmp_ge_u32_e32 vcc, v3, v2
	v_add_u32_e32 v3, 1, v5
	s_nop 0
	v_cndmask_b32_e32 v1, v1, v4, vcc
	v_mul_lo_u32 v4, v2, v1
	v_add_u32_e32 v2, v4, v2
	v_cmp_ne_u32_e32 vcc, v3, v2
	s_and_saveexec_b64 s[6:7], vcc
	s_xor_b64 s[38:39], exec, s[6:7]
	s_cbranch_execz .LBB0_363
	s_waitcnt lgkmcnt(0)
	v_mov_b32_e32 v0, 0x3100
	global_load_dword v0, v0, s[56:57] offset:1024 sc1
	s_add_u32 s42, s56, 0x3500
	s_addc_u32 s43, s57, 0
	s_waitcnt vmcnt(0)
	v_cmp_eq_u32_e32 vcc, v0, v1
	s_and_saveexec_b64 s[40:41], vcc
	s_cbranch_execz .LBB0_362
	s_mov_b32 s6, 1
	s_mov_b64 s[44:45], 0
	v_mov_b32_e32 v0, 0
	s_branch .LBB0_353

.LBB0_453:
	s_or_b64 exec, exec, s[36:37]
	v_cvt_f32_u32_e32 v4, v2
	s_waitcnt vmcnt(0)
	v_readfirstlane_b32 s0, v3
	v_sub_u32_e32 v3, 0, v2
	v_rcp_iflag_f32_e32 v4, v4
	v_add_u32_e32 v5, s0, v1
	v_mul_f32_e32 v4, 0x4f7ffffe, v4
	v_cvt_u32_f32_e32 v4, v4
	v_mul_lo_u32 v1, v3, v4
	v_mul_hi_u32 v1, v4, v1
	v_add_u32_e32 v1, v4, v1
	v_mul_hi_u32 v1, v5, v1
	v_mul_lo_u32 v3, v1, v2
	v_sub_u32_e32 v3, v5, v3
	v_add_u32_e32 v4, 1, v1
	v_cmp_ge_u32_e32 vcc, v3, v2
	s_nop 1
	v_cndmask_b32_e32 v1, v1, v4, vcc
	v_sub_u32_e32 v4, v3, v2
	v_cndmask_b32_e32 v3, v3, v4, vcc
	v_add_u32_e32 v4, 1, v1
	v_cmp_ge_u32_e32 vcc, v3, v2
	v_add_u32_e32 v3, 1, v5
	s_nop 0
	v_cndmask_b32_e32 v1, v1, v4, vcc
	v_mul_lo_u32 v4, v2, v1
	v_add_u32_e32 v2, v4, v2
	v_cmp_ne_u32_e32 vcc, v3, v2
	s_and_saveexec_b64 s[0:1], vcc
	s_xor_b64 s[26:27], exec, s[0:1]
	s_cbranch_execz .LBB0_467
	s_waitcnt lgkmcnt(0)
	v_mov_b32_e32 v0, 0x3100
	global_load_dword v0, v0, s[56:57] offset:1024 sc1
	s_add_u32 s38, s56, 0x3500
	s_addc_u32 s39, s57, 0
	s_waitcnt vmcnt(0)
	v_cmp_eq_u32_e32 vcc, v0, v1
	s_and_saveexec_b64 s[36:37], vcc
	s_cbranch_execz .LBB0_466
	s_mov_b32 s0, 1
	s_mov_b64 s[40:41], 0
	v_mov_b32_e32 v0, 0
	s_branch .LBB0_457

.LBB0_545:
	s_or_b64 exec, exec, s[34:35]
	v_cvt_f32_u32_e32 v4, v2
	s_waitcnt vmcnt(0)
	v_readfirstlane_b32 s0, v3
	v_sub_u32_e32 v3, 0, v2
	v_rcp_iflag_f32_e32 v4, v4
	v_add_u32_e32 v5, s0, v1
	v_mul_f32_e32 v4, 0x4f7ffffe, v4
	v_cvt_u32_f32_e32 v4, v4
	v_mul_lo_u32 v1, v3, v4
	v_mul_hi_u32 v1, v4, v1
	v_add_u32_e32 v1, v4, v1
	v_mul_hi_u32 v1, v5, v1
	v_mul_lo_u32 v3, v1, v2
	v_sub_u32_e32 v3, v5, v3
	v_add_u32_e32 v4, 1, v1
	v_cmp_ge_u32_e32 vcc, v3, v2
	s_nop 1
	v_cndmask_b32_e32 v1, v1, v4, vcc
	v_sub_u32_e32 v4, v3, v2
	v_cndmask_b32_e32 v3, v3, v4, vcc
	v_add_u32_e32 v4, 1, v1
	v_cmp_ge_u32_e32 vcc, v3, v2
	v_add_u32_e32 v3, 1, v5
	s_nop 0
	v_cndmask_b32_e32 v1, v1, v4, vcc
	v_mul_lo_u32 v4, v2, v1
	v_add_u32_e32 v2, v4, v2
	v_cmp_ne_u32_e32 vcc, v3, v2
	s_and_saveexec_b64 s[0:1], vcc
	s_xor_b64 s[26:27], exec, s[0:1]
	s_cbranch_execz .LBB0_559
	s_waitcnt lgkmcnt(0)
	v_mov_b32_e32 v0, 0x3100
	global_load_dword v0, v0, s[56:57] offset:1024 sc1
	s_add_u32 s36, s56, 0x3500
	s_addc_u32 s37, s57, 0
	s_waitcnt vmcnt(0)
	v_cmp_eq_u32_e32 vcc, v0, v1
	s_and_saveexec_b64 s[34:35], vcc
	s_cbranch_execz .LBB0_558
	s_mov_b32 s0, 1
	s_mov_b64 s[38:39], 0
	v_mov_b32_e32 v0, 0
	s_branch .LBB0_549

.LBB0_653:
	s_or_b64 exec, exec, s[26:27]
	v_cvt_f32_u32_e32 v4, v2
	s_waitcnt vmcnt(0)
	v_readfirstlane_b32 s0, v3
	v_sub_u32_e32 v3, 0, v2
	v_rcp_iflag_f32_e32 v4, v4
	v_add_u32_e32 v5, s0, v1
	v_mul_f32_e32 v4, 0x4f7ffffe, v4
	v_cvt_u32_f32_e32 v4, v4
	v_mul_lo_u32 v1, v3, v4
	v_mul_hi_u32 v1, v4, v1
	v_add_u32_e32 v1, v4, v1
	v_mul_hi_u32 v1, v5, v1
	v_mul_lo_u32 v3, v1, v2
	v_sub_u32_e32 v3, v5, v3
	v_add_u32_e32 v4, 1, v1
	v_cmp_ge_u32_e32 vcc, v3, v2
	s_nop 1
	v_cndmask_b32_e32 v1, v1, v4, vcc
	v_sub_u32_e32 v4, v3, v2
	v_cndmask_b32_e32 v3, v3, v4, vcc
	v_add_u32_e32 v4, 1, v1
	v_cmp_ge_u32_e32 vcc, v3, v2
	v_add_u32_e32 v3, 1, v5
	s_nop 0
	v_cndmask_b32_e32 v1, v1, v4, vcc
	v_mul_lo_u32 v4, v2, v1
	v_add_u32_e32 v2, v4, v2
	v_cmp_ne_u32_e32 vcc, v3, v2
	s_and_saveexec_b64 s[0:1], vcc
	s_xor_b64 s[22:23], exec, s[0:1]
	s_cbranch_execz .LBB0_667
	s_waitcnt lgkmcnt(0)
	v_mov_b32_e32 v0, 0x3100
	global_load_dword v0, v0, s[56:57] offset:1024 sc1
	s_add_u32 s34, s56, 0x3500
	s_addc_u32 s35, s57, 0
	s_waitcnt vmcnt(0)
	v_cmp_eq_u32_e32 vcc, v0, v1
	s_and_saveexec_b64 s[26:27], vcc
	s_cbranch_execz .LBB0_666
	s_mov_b32 s0, 1
	s_mov_b64 s[36:37], 0
	v_mov_b32_e32 v0, 0
	s_branch .LBB0_657

.LBB0_750:
	s_or_b64 exec, exec, s[24:25]
	v_cvt_f32_u32_e32 v4, v2
	s_waitcnt vmcnt(0)
	v_readfirstlane_b32 s0, v3
	v_sub_u32_e32 v3, 0, v2
	v_rcp_iflag_f32_e32 v4, v4
	v_add_u32_e32 v5, s0, v1
	v_mul_f32_e32 v4, 0x4f7ffffe, v4
	v_cvt_u32_f32_e32 v4, v4
	v_mul_lo_u32 v1, v3, v4
	v_mul_hi_u32 v1, v4, v1
	v_add_u32_e32 v1, v4, v1
	v_mul_hi_u32 v1, v5, v1
	v_mul_lo_u32 v3, v1, v2
	v_sub_u32_e32 v3, v5, v3
	v_add_u32_e32 v4, 1, v1
	v_cmp_ge_u32_e32 vcc, v3, v2
	s_nop 1
	v_cndmask_b32_e32 v1, v1, v4, vcc
	v_sub_u32_e32 v4, v3, v2
	v_cndmask_b32_e32 v3, v3, v4, vcc
	v_add_u32_e32 v4, 1, v1
	v_cmp_ge_u32_e32 vcc, v3, v2
	v_add_u32_e32 v3, 1, v5
	s_nop 0
	v_cndmask_b32_e32 v1, v1, v4, vcc
	v_mul_lo_u32 v4, v2, v1
	v_add_u32_e32 v2, v4, v2
	v_cmp_ne_u32_e32 vcc, v3, v2
	s_and_saveexec_b64 s[0:1], vcc
	s_xor_b64 s[18:19], exec, s[0:1]
	s_cbranch_execz .LBB0_764
	s_waitcnt lgkmcnt(0)
	v_mov_b32_e32 v0, 0x3100
	global_load_dword v0, v0, s[56:57] offset:1024 sc1
	s_add_u32 s26, s56, 0x3500
	s_addc_u32 s27, s57, 0
	s_waitcnt vmcnt(0)
	v_cmp_eq_u32_e32 vcc, v0, v1
	s_and_saveexec_b64 s[24:25], vcc
	s_cbranch_execz .LBB0_763
	s_mov_b32 s0, 1
	s_mov_b64 s[34:35], 0
	v_mov_b32_e32 v0, 0
	s_branch .LBB0_754

.LBB0_818:
	s_or_b64 exec, exec, s[20:21]
	v_cvt_f32_u32_e32 v4, v2
	s_waitcnt vmcnt(0)
	v_readfirstlane_b32 s0, v3
	v_sub_u32_e32 v3, 0, v2
	v_rcp_iflag_f32_e32 v4, v4
	v_add_u32_e32 v5, s0, v1
	v_mul_f32_e32 v4, 0x4f7ffffe, v4
	v_cvt_u32_f32_e32 v4, v4
	v_mul_lo_u32 v1, v3, v4
	v_mul_hi_u32 v1, v4, v1
	v_add_u32_e32 v1, v4, v1
	v_mul_hi_u32 v1, v5, v1
	v_mul_lo_u32 v3, v1, v2
	v_sub_u32_e32 v3, v5, v3
	v_add_u32_e32 v4, 1, v1
	v_cmp_ge_u32_e32 vcc, v3, v2
	s_nop 1
	v_cndmask_b32_e32 v1, v1, v4, vcc
	v_sub_u32_e32 v4, v3, v2
	v_cndmask_b32_e32 v3, v3, v4, vcc
	v_add_u32_e32 v4, 1, v1
	v_cmp_ge_u32_e32 vcc, v3, v2
	v_add_u32_e32 v3, 1, v5
	s_nop 0
	v_cndmask_b32_e32 v1, v1, v4, vcc
	v_mul_lo_u32 v4, v2, v1
	v_add_u32_e32 v2, v4, v2
	v_cmp_ne_u32_e32 vcc, v3, v2
	s_and_saveexec_b64 s[0:1], vcc
	s_xor_b64 s[18:19], exec, s[0:1]
	s_cbranch_execz .LBB0_832
	s_waitcnt lgkmcnt(0)
	v_mov_b32_e32 v0, 0x3100
	global_load_dword v0, v0, s[56:57] offset:1024 sc1
	s_add_u32 s22, s56, 0x3500
	s_addc_u32 s23, s57, 0
	s_waitcnt vmcnt(0)
	v_cmp_eq_u32_e32 vcc, v0, v1
	s_and_saveexec_b64 s[20:21], vcc
	s_cbranch_execz .LBB0_831
	s_mov_b32 s0, 1
	s_mov_b64 s[24:25], 0
	v_mov_b32_e32 v0, 0
	s_branch .LBB0_822

.LBB0_916:
	s_or_b64 exec, exec, s[8:9]
	v_cvt_f32_u32_e32 v4, v2
	s_waitcnt vmcnt(0)
	v_readfirstlane_b32 s3, v3
	v_sub_u32_e32 v3, 0, v2
	v_rcp_iflag_f32_e32 v4, v4
	v_add_u32_e32 v5, s3, v1
	v_mul_f32_e32 v4, 0x4f7ffffe, v4
	v_cvt_u32_f32_e32 v4, v4
	v_mul_lo_u32 v1, v3, v4
	v_mul_hi_u32 v1, v4, v1
	v_add_u32_e32 v1, v4, v1
	v_mul_hi_u32 v1, v5, v1
	v_mul_lo_u32 v3, v1, v2
	v_sub_u32_e32 v3, v5, v3
	v_add_u32_e32 v4, 1, v1
	v_cmp_ge_u32_e32 vcc, v3, v2
	s_nop 1
	v_cndmask_b32_e32 v1, v1, v4, vcc
	v_sub_u32_e32 v4, v3, v2
	v_cndmask_b32_e32 v3, v3, v4, vcc
	v_add_u32_e32 v4, 1, v1
	v_cmp_ge_u32_e32 vcc, v3, v2
	v_add_u32_e32 v3, 1, v5
	s_nop 0
	v_cndmask_b32_e32 v1, v1, v4, vcc
	v_mul_lo_u32 v4, v2, v1
	v_add_u32_e32 v2, v4, v2
	v_cmp_ne_u32_e32 vcc, v3, v2
	s_and_saveexec_b64 s[6:7], vcc
	s_xor_b64 s[6:7], exec, s[6:7]
	s_cbranch_execz .LBB0_930
	s_waitcnt lgkmcnt(0)
	v_mov_b32_e32 v0, 0x3100
	global_load_dword v0, v0, s[56:57] offset:1024 sc1
	s_add_u32 s10, s56, 0x3500
	s_addc_u32 s11, s57, 0
	s_waitcnt vmcnt(0)
	v_cmp_eq_u32_e32 vcc, v0, v1
	s_and_saveexec_b64 s[8:9], vcc
	s_cbranch_execz .LBB0_929
	s_mov_b32 s3, 1
	s_mov_b64 s[14:15], 0
	v_mov_b32_e32 v0, 0
	s_branch .LBB0_920
